# g2 + sliding-window sink logit from a spill lane (no vmcnt(0) in the head body) + rope-partner query gains from LDS: next kv-head K/V prefetch and next-head Q loads are no longer drained early
# speedup vs baseline: 1.0265x; 1.0060x over previous
.LBB0_176:
	s_and_b32 s0, s57, 7
	v_writelane_b32 v243, s57, 7
	s_ashr_i32 s1, s57, 3
	v_writelane_b32 v243, s0, 8
	s_lshl_b32 s0, s0, 12
	s_lshl_b32 s2, s1, 7
	v_mov_b32_e32 v36, v0
	s_add_i32 s20, s2, s0
	s_barrier
	v_readlane_b32 s94, v244, 20
	v_readlane_b32 s95, v244, 21
	v_and_b32_e32 v4, 63, v0
	v_lshlrev_b32_e32 v4, 2, v4
	s_nop 4
	global_load_dword v129, v4, s[94:95]
	v_readlane_b32 s90, v244, 18
	v_readlane_b32 s91, v244, 19
	s_nop 4
	global_load_dword v223, v4, s[90:91]
	s_cmp_gt_i32 s1, 0
	v_ashrrev_i32_e32 v50, 1, v36
	s_cselect_b64 s[22:23], -1, 0
	v_cmp_lt_i32_e32 vcc, s84, v50
	v_writelane_b32 v243, s1, 9
	s_or_b64 s[0:1], s[22:23], vcc
	v_and_b32_e32 v54, 1, v36
	v_writelane_b32 v243, s0, 10
	v_ashrrev_i32_e32 v51, 31, v50
	v_lshlrev_b32_e32 v2, 5, v54
	v_writelane_b32 v243, s1, 11
	s_xor_b64 s[0:1], s[0:1], -1
	s_and_saveexec_b64 s[4:5], s[0:1]
	s_xor_b64 s[0:1], exec, s[4:5]
	s_ashr_i32 s21, s20, 31
	v_lshl_add_u64 v[4:5], v[50:51], 0, s[20:21]
	v_lshlrev_b32_e32 v2, 5, v54
	v_mad_u64_u32 v[52:53], s[4:5], v4, s92, 0
	v_mad_i32_i24 v53, v5, s92, v53
	v_mov_b32_e32 v55, v2
	v_mov_b64_e32 v[48:49], v[2:3]
	s_or_saveexec_b64 s[0:1], s[0:1]
	v_mov_b32_e32 v110, 0
	s_mov_b32 s33, 0
	v_mov_b32_e32 v24, 0
	v_mov_b32_e32 v25, 0
	v_mov_b32_e32 v26, 0
	v_mov_b32_e32 v27, 0
	v_mov_b32_e32 v28, 0
	v_mov_b32_e32 v29, 0
	v_mov_b32_e32 v30, 0
	v_mov_b32_e32 v31, 0
	v_mov_b32_e32 v32, 0
	v_mov_b32_e32 v33, 0
	v_mov_b32_e32 v34, 0
	v_mov_b32_e32 v35, 0
	v_mov_b32_e32 v20, 0
	v_mov_b32_e32 v21, 0
	v_mov_b32_e32 v22, 0
	v_mov_b32_e32 v23, 0
	v_mov_b32_e32 v4, 0
	v_mov_b32_e32 v5, 0
	v_mov_b32_e32 v6, 0
	v_mov_b32_e32 v7, 0
	v_mov_b32_e32 v12, 0
	v_mov_b32_e32 v13, 0
	v_mov_b32_e32 v14, 0
	v_mov_b32_e32 v15, 0
	v_mov_b32_e32 v8, 0
	v_mov_b32_e32 v9, 0
	v_mov_b32_e32 v10, 0
	v_mov_b32_e32 v11, 0
	v_mov_b32_e32 v16, 0
	v_mov_b32_e32 v17, 0
	v_mov_b32_e32 v18, 0
	v_mov_b32_e32 v19, 0
	s_xor_b64 exec, exec, s[0:1]
	s_cbranch_execz .LBB0_180
	s_ashr_i32 s21, s20, 31
	v_lshl_add_u64 v[38:39], v[50:51], 0, s[20:21]
	v_mov_b64_e32 v[4:5], s[88:89]
	v_mad_u64_u32 v[4:5], s[4:5], v38, s92, v[4:5]
	v_mad_i32_i24 v5, v39, s92, v5
	v_lshlrev_b32_e32 v6, 6, v54
	v_mov_b32_e32 v7, v3
	s_mov_b32 s4, 0xfff70b00
	v_lshl_add_u64 v[4:5], v[4:5], 0, v[6:7]
	s_mov_b32 s5, -1
	v_lshl_add_u64 v[20:21], v[4:5], 0, s[4:5]
	s_mov_b32 s4, 0xfff70a00
	s_mov_b32 s3, 0xfff71000
	s_mov_b32 s5, -1
	v_add_co_u32_e32 v14, vcc, s3, v4
	v_lshl_add_u64 v[12:13], v[4:5], 0, s[4:5]
	s_nop 0
	v_addc_co_u32_e32 v15, vcc, -1, v5, vcc
	global_load_dwordx4 v[8:11], v[12:13], off offset:32
	global_load_dwordx4 v[16:19], v[12:13], off offset:48
	global_load_dwordx4 v[4:7], v[14:15], off offset:-1536
	global_load_dwordx4 v[24:27], v[14:15], off offset:-1280
	global_load_dwordx4 v[28:31], v[20:21], off offset:16
	global_load_dwordx4 v[32:35], v[20:21], off offset:32
	s_nop 0
	global_load_dwordx4 v[12:15], v[12:13], off offset:16
	s_nop 0
	global_load_dwordx4 v[20:23], v[20:21], off offset:48
	v_mad_u64_u32 v[52:53], s[4:5], v38, s92, 0
	v_mad_i32_i24 v53, v39, s92, v53
	v_mov_b64_e32 v[48:49], v[2:3]
	v_mov_b32_e32 v55, v2
.LBB0_180:
	s_or_b64 exec, exec, s[0:1]
	v_and_b32_e32 v37, 64, v182
	v_ashrrev_i32_e32 v59, 6, v36
	v_bfe_u32 v51, v36, 4, 2
	v_and_b32_e32 v56, 15, v36
	v_xor_b32_e32 v36, 1, v182
	v_add_u32_e32 v37, 64, v37
	v_cmp_lt_i32_e32 vcc, v36, v37
	v_lshlrev_b32_e32 v2, 4, v59
	v_min_i32_e32 v57, 6, v59
	v_and_b32_e32 v57, -2, v57
	v_cndmask_b32_e32 v61, v182, v36, vcc
	v_xor_b32_e32 v36, 16, v182
	v_cmp_lt_i32_e32 vcc, v36, v37
	v_lshlrev_b32_e32 v111, 2, v51
	v_lshlrev_b32_e32 v68, 4, v57
	v_cndmask_b32_e32 v66, v182, v36, vcc
	v_xor_b32_e32 v36, 32, v182
	v_cmp_lt_i32_e32 vcc, v36, v37
	v_or_b32_e32 v38, v68, v111
	s_movk_i32 s3, 0x7e
	v_cndmask_b32_e32 v67, v182, v36, vcc
	v_cmp_eq_u32_e32 vcc, 1, v51
	v_or_b32_e32 v39, 2, v38
	v_add_u32_e32 v69, 16, v68
	v_cndmask_b32_e64 v36, 0, 1.0, vcc
	v_cmp_ne_u32_e32 vcc, 0, v51
	v_add_u32_e32 v70, 2, v57
	v_lshlrev_b32_e32 v71, 4, v70
	v_cndmask_b32_e32 v114, -1.0, v36, vcc
	v_or_b32_e32 v36, v2, v56
	v_add_u32_e32 v37, 0x80, v36
	v_cmp_gt_i32_e32 vcc, v38, v36
	v_cmp_le_i32_e64 s[0:1], v38, v37
	s_and_b64 s[0:1], vcc, s[0:1]
	v_cmp_lt_i32_e32 vcc, s84, v38
	s_or_b64 s[4:5], s[22:23], vcc
	s_and_b64 s[0:1], s[0:1], s[4:5]
	v_cmp_ge_i32_e32 vcc, v38, v36
	v_cmp_lt_i32_e64 s[4:5], v38, v37
	s_and_b64 s[4:5], vcc, s[4:5]
	v_cmp_lt_i32_e32 vcc, s3, v38
	v_writelane_b32 v243, s0, 12
	s_or_b64 s[6:7], s[22:23], vcc
	v_cmp_gt_i32_e32 vcc, v39, v36
	v_writelane_b32 v243, s1, 13
	s_and_b64 s[0:1], s[4:5], s[6:7]
	v_cmp_le_i32_e64 s[6:7], v39, v37
	s_and_b64 s[6:7], vcc, s[6:7]
	v_cmp_lt_i32_e32 vcc, s84, v39
	v_writelane_b32 v243, s0, 14
	s_or_b64 s[8:9], s[22:23], vcc
	v_or_b32_e32 v38, 3, v38
	v_writelane_b32 v243, s1, 15
	s_and_b64 s[0:1], s[6:7], s[8:9]
	v_cmp_gt_i32_e32 vcc, v38, v36
	v_cmp_le_i32_e64 s[8:9], v38, v37
	s_and_b64 s[8:9], vcc, s[8:9]
	v_cmp_lt_i32_e32 vcc, s84, v38
	v_writelane_b32 v243, s0, 16
	s_or_b64 s[10:11], s[22:23], vcc
	v_or_b32_e32 v38, v69, v111
	v_writelane_b32 v243, s1, 17
	s_and_b64 s[0:1], s[8:9], s[10:11]
	v_cmp_gt_i32_e32 vcc, v38, v36
	v_cmp_le_i32_e64 s[10:11], v38, v37
	s_and_b64 s[10:11], vcc, s[10:11]
	v_cmp_lt_i32_e32 vcc, s84, v38
	v_writelane_b32 v243, s0, 18
	s_or_b64 s[12:13], s[22:23], vcc
	v_cmp_ge_i32_e32 vcc, v38, v36
	v_writelane_b32 v243, s1, 19
	s_and_b64 s[0:1], s[10:11], s[12:13]
	v_cmp_lt_i32_e64 s[12:13], v38, v37
	s_and_b64 s[12:13], vcc, s[12:13]
	v_cmp_lt_i32_e32 vcc, s3, v38
	v_writelane_b32 v243, s0, 20
	s_or_b64 s[14:15], s[22:23], vcc
	v_or_b32_e32 v39, 2, v38
	v_writelane_b32 v243, s1, 21
	s_and_b64 s[0:1], s[12:13], s[14:15]
	v_cmp_gt_i32_e32 vcc, v39, v36
	v_cmp_le_i32_e64 s[14:15], v39, v37
	s_and_b64 s[14:15], vcc, s[14:15]
	v_cmp_lt_i32_e32 vcc, s84, v39
	v_writelane_b32 v243, s0, 22
	s_or_b64 s[16:17], s[22:23], vcc
	v_or_b32_e32 v38, 3, v38
	v_writelane_b32 v243, s1, 23
	s_and_b64 s[0:1], s[14:15], s[16:17]
	v_cmp_gt_i32_e32 vcc, v38, v36
	v_cmp_le_i32_e64 s[16:17], v38, v37
	s_and_b64 s[16:17], vcc, s[16:17]
	v_cmp_lt_i32_e32 vcc, s84, v38
	v_writelane_b32 v243, s0, 24
	s_or_b64 s[18:19], s[22:23], vcc
	v_or_b32_e32 v38, v71, v111
	v_writelane_b32 v243, s1, 25
	s_and_b64 s[0:1], s[16:17], s[18:19]
	v_cmp_gt_i32_e32 vcc, v38, v36
	v_cmp_le_i32_e64 s[18:19], v38, v37
	s_and_b64 s[18:19], vcc, s[18:19]
	v_cmp_lt_i32_e32 vcc, s84, v38
	v_writelane_b32 v243, s0, 26
	s_mov_b32 s4, s20
	s_or_b64 s[20:21], s[22:23], vcc
	v_writelane_b32 v243, s1, 27
	s_and_b64 s[0:1], s[18:19], s[20:21]
	v_cmp_ge_i32_e32 vcc, v38, v36
	v_cmp_lt_i32_e64 s[20:21], v38, v37
	s_and_b64 s[20:21], vcc, s[20:21]
	v_cmp_lt_i32_e32 vcc, s3, v38
	s_mov_b64 s[6:7], s[22:23]
	s_or_b64 s[22:23], s[22:23], vcc
	v_or_b32_e32 v39, 2, v38
	s_and_b64 s[20:21], s[20:21], s[22:23]
	v_cmp_gt_i32_e32 vcc, v39, v36
	v_cmp_le_i32_e64 s[22:23], v39, v37
	s_and_b64 s[22:23], vcc, s[22:23]
	v_cmp_lt_i32_e32 vcc, s84, v39
	s_or_b64 s[24:25], s[6:7], vcc
	v_or_b32_e32 v38, 3, v38
	s_and_b64 s[22:23], s[22:23], s[24:25]
	v_cmp_gt_i32_e32 vcc, v38, v36
	v_cmp_le_i32_e64 s[24:25], v38, v37
	v_add_u32_e32 v72, 48, v68
	s_and_b64 s[24:25], vcc, s[24:25]
	v_cmp_lt_i32_e32 vcc, s84, v38
	s_or_b64 s[26:27], s[6:7], vcc
	v_or_b32_e32 v38, v72, v111
	s_and_b64 s[24:25], s[24:25], s[26:27]
	v_cmp_gt_i32_e32 vcc, v38, v36
	v_cmp_le_i32_e64 s[26:27], v38, v37
	s_and_b64 s[26:27], vcc, s[26:27]
	v_cmp_lt_i32_e32 vcc, s84, v38
	s_or_b64 s[28:29], s[6:7], vcc
	s_and_b64 s[26:27], s[26:27], s[28:29]
	v_cmp_ge_i32_e32 vcc, v38, v36
	v_cmp_lt_i32_e64 s[28:29], v38, v37
	s_and_b64 s[28:29], vcc, s[28:29]
	v_cmp_lt_i32_e32 vcc, s3, v38
	s_or_b64 s[30:31], s[6:7], vcc
	v_or_b32_e32 v39, 2, v38
	s_and_b64 s[28:29], s[28:29], s[30:31]
	v_cmp_gt_i32_e32 vcc, v39, v36
	v_cmp_le_i32_e64 s[30:31], v39, v37
	s_and_b64 s[30:31], vcc, s[30:31]
	v_cmp_lt_i32_e32 vcc, s84, v39
	s_or_b64 s[34:35], s[6:7], vcc
	v_or_b32_e32 v38, 3, v38
	v_add_u32_e32 v73, 4, v57
	s_and_b64 s[30:31], s[30:31], s[34:35]
	v_cmp_gt_i32_e32 vcc, v38, v36
	v_cmp_le_i32_e64 s[34:35], v38, v37
	v_lshlrev_b32_e32 v74, 4, v73
	s_and_b64 s[34:35], vcc, s[34:35]
	v_cmp_lt_i32_e32 vcc, s84, v38
	s_or_b64 s[36:37], s[6:7], vcc
	v_or_b32_e32 v38, v74, v111
	s_and_b64 s[34:35], s[34:35], s[36:37]
	v_cmp_gt_i32_e32 vcc, v38, v36
	v_cmp_le_i32_e64 s[36:37], v38, v37
	s_and_b64 s[36:37], vcc, s[36:37]
	v_cmp_lt_i32_e32 vcc, s84, v38
	s_or_b64 s[38:39], s[6:7], vcc
	s_and_b64 s[36:37], s[36:37], s[38:39]
	v_cmp_ge_i32_e32 vcc, v38, v36
	v_cmp_lt_i32_e64 s[38:39], v38, v37
	s_and_b64 s[38:39], vcc, s[38:39]
	v_cmp_lt_i32_e32 vcc, s3, v38
	s_or_b64 s[40:41], s[6:7], vcc
	v_or_b32_e32 v39, 2, v38
	s_and_b64 s[38:39], s[38:39], s[40:41]
	v_cmp_gt_i32_e32 vcc, v39, v36
	v_cmp_le_i32_e64 s[40:41], v39, v37
	s_and_b64 s[40:41], vcc, s[40:41]
	v_cmp_lt_i32_e32 vcc, s84, v39
	s_or_b64 s[42:43], s[6:7], vcc
	v_or_b32_e32 v38, 3, v38
	s_and_b64 s[40:41], s[40:41], s[42:43]
	v_cmp_gt_i32_e32 vcc, v38, v36
	v_cmp_le_i32_e64 s[42:43], v38, v37
	v_add_u32_e32 v75, 0x50, v68
	s_and_b64 s[42:43], vcc, s[42:43]
	v_cmp_lt_i32_e32 vcc, s84, v38
	s_or_b64 s[44:45], s[6:7], vcc
	v_or_b32_e32 v38, v75, v111
	s_and_b64 s[42:43], s[42:43], s[44:45]
	v_cmp_gt_i32_e32 vcc, v38, v36
	v_cmp_le_i32_e64 s[44:45], v38, v37
	s_and_b64 s[44:45], vcc, s[44:45]
	v_cmp_lt_i32_e32 vcc, s84, v38
	s_or_b64 s[46:47], s[6:7], vcc
	s_and_b64 s[44:45], s[44:45], s[46:47]
	v_cmp_ge_i32_e32 vcc, v38, v36
	v_cmp_lt_i32_e64 s[46:47], v38, v37
	s_and_b64 s[46:47], vcc, s[46:47]
	v_cmp_lt_i32_e32 vcc, s3, v38
	s_or_b64 s[48:49], s[6:7], vcc
	v_or_b32_e32 v39, 2, v38
	s_and_b64 s[46:47], s[46:47], s[48:49]
	v_cmp_gt_i32_e32 vcc, v39, v36
	v_cmp_le_i32_e64 s[48:49], v39, v37
	s_and_b64 s[48:49], vcc, s[48:49]
	v_cmp_lt_i32_e32 vcc, s84, v39
	s_or_b64 s[50:51], s[6:7], vcc
	v_or_b32_e32 v38, 3, v38
	v_add_u32_e32 v76, 6, v57
	s_and_b64 s[48:49], s[48:49], s[50:51]
	v_cmp_gt_i32_e32 vcc, v38, v36
	v_cmp_le_i32_e64 s[50:51], v38, v37
	v_lshlrev_b32_e32 v77, 4, v76
	s_and_b64 s[50:51], vcc, s[50:51]
	v_cmp_lt_i32_e32 vcc, s84, v38
	s_or_b64 s[52:53], s[6:7], vcc
	v_or_b32_e32 v38, v77, v111
	s_and_b64 s[50:51], s[50:51], s[52:53]
	v_cmp_gt_i32_e32 vcc, v38, v36
	v_cmp_le_i32_e64 s[52:53], v38, v37
	s_and_b64 s[52:53], vcc, s[52:53]
	v_cmp_lt_i32_e32 vcc, s84, v38
	s_or_b64 s[54:55], s[6:7], vcc
	s_and_b64 s[52:53], s[52:53], s[54:55]
	v_cmp_ge_i32_e32 vcc, v38, v36
	v_cmp_lt_i32_e64 s[54:55], v38, v37
	s_and_b64 s[54:55], vcc, s[54:55]
	v_cmp_lt_i32_e32 vcc, s3, v38
	s_or_b64 s[56:57], s[6:7], vcc
	v_or_b32_e32 v39, 2, v38
	s_and_b64 s[54:55], s[54:55], s[56:57]
	v_cmp_gt_i32_e32 vcc, v39, v36
	v_cmp_le_i32_e64 s[56:57], v39, v37
	s_and_b64 s[56:57], vcc, s[56:57]
	v_cmp_lt_i32_e32 vcc, s84, v39
	s_or_b64 s[58:59], s[6:7], vcc
	v_or_b32_e32 v38, 3, v38
	s_and_b64 s[56:57], s[56:57], s[58:59]
	v_cmp_gt_i32_e32 vcc, v38, v36
	v_cmp_le_i32_e64 s[58:59], v38, v37
	v_add_u32_e32 v78, 0x70, v68
	s_and_b64 s[58:59], vcc, s[58:59]
	v_cmp_lt_i32_e32 vcc, s84, v38
	s_or_b64 s[60:61], s[6:7], vcc
	v_or_b32_e32 v38, v78, v111
	s_and_b64 s[58:59], s[58:59], s[60:61]
	v_cmp_gt_i32_e32 vcc, v38, v36
	v_cmp_le_i32_e64 s[60:61], v38, v37
	s_and_b64 s[60:61], vcc, s[60:61]
	v_cmp_lt_i32_e32 vcc, s84, v38
	s_or_b64 s[62:63], s[6:7], vcc
	s_and_b64 s[60:61], s[60:61], s[62:63]
	v_cmp_ge_i32_e32 vcc, v38, v36
	v_cmp_lt_i32_e64 s[62:63], v38, v37
	s_and_b64 s[62:63], vcc, s[62:63]
	v_cmp_lt_i32_e32 vcc, s3, v38
	s_or_b64 s[64:65], s[6:7], vcc
	v_or_b32_e32 v39, 2, v38
	s_and_b64 s[62:63], s[62:63], s[64:65]
	v_cmp_gt_i32_e32 vcc, v39, v36
	v_cmp_le_i32_e64 s[64:65], v39, v37
	s_and_b64 s[64:65], vcc, s[64:65]
	v_cmp_lt_i32_e32 vcc, s84, v39
	s_or_b64 s[66:67], s[6:7], vcc
	v_or_b32_e32 v38, 3, v38
	s_and_b64 s[64:65], s[64:65], s[66:67]
	v_cmp_gt_i32_e32 vcc, v38, v36
	v_cmp_le_i32_e64 s[66:67], v38, v37
	v_add_u32_e32 v79, 8, v57
	s_and_b64 s[66:67], vcc, s[66:67]
	v_cmp_lt_i32_e32 vcc, s84, v38
	v_lshlrev_b32_e32 v98, 4, v79
	s_or_b64 s[68:69], s[6:7], vcc
	v_or_b32_e32 v38, v98, v111
	s_and_b64 s[66:67], s[66:67], s[68:69]
	v_cmp_gt_i32_e32 vcc, v38, v36
	v_cmp_le_i32_e64 s[68:69], v38, v37
	s_and_b64 s[68:69], vcc, s[68:69]
	v_cmp_lt_i32_e32 vcc, s84, v38
	s_or_b64 s[70:71], s[6:7], vcc
	s_and_b64 s[68:69], s[68:69], s[70:71]
	v_cmp_ge_i32_e32 vcc, v38, v36
	v_cmp_lt_i32_e64 s[70:71], v38, v37
	s_and_b64 s[70:71], vcc, s[70:71]
	v_cmp_lt_i32_e32 vcc, s3, v38
	s_or_b64 s[72:73], s[6:7], vcc
	v_or_b32_e32 v39, 2, v38
	s_and_b64 s[70:71], s[70:71], s[72:73]
	v_cmp_gt_i32_e32 vcc, v39, v36
	v_cmp_le_i32_e64 s[72:73], v39, v37
	s_and_b64 s[72:73], vcc, s[72:73]
	v_cmp_lt_i32_e32 vcc, s84, v39
	s_or_b64 s[74:75], s[6:7], vcc
	v_or_b32_e32 v38, 3, v38
	s_and_b64 s[72:73], s[72:73], s[74:75]
	v_cmp_gt_i32_e32 vcc, v38, v36
	v_cmp_le_i32_e64 s[74:75], v38, v37
	s_and_b64 s[74:75], vcc, s[74:75]
	v_cmp_lt_i32_e32 vcc, s84, v38
	v_add_u32_e32 v99, 0x90, v68
	s_or_b64 s[76:77], s[6:7], vcc
	v_or_b32_e32 v38, v99, v111
	s_and_b64 s[74:75], s[74:75], s[76:77]
	v_cmp_gt_i32_e32 vcc, v38, v36
	v_cmp_le_i32_e64 s[76:77], v38, v37
	s_and_b64 s[76:77], vcc, s[76:77]
	v_cmp_lt_i32_e32 vcc, s84, v38
	s_or_b64 s[78:79], s[6:7], vcc
	s_and_b64 s[76:77], s[76:77], s[78:79]
	v_cmp_ge_i32_e32 vcc, v38, v36
	v_cmp_lt_i32_e64 s[78:79], v38, v37
	s_and_b64 s[78:79], vcc, s[78:79]
	v_cmp_lt_i32_e32 vcc, s3, v38
	s_or_b64 s[80:81], s[6:7], vcc
	v_or_b32_e32 v39, 2, v38
	s_and_b64 s[78:79], s[78:79], s[80:81]
	v_cmp_gt_i32_e32 vcc, v39, v36
	v_cmp_le_i32_e64 s[80:81], v39, v37
	s_and_b64 s[80:81], vcc, s[80:81]
	v_cmp_lt_i32_e32 vcc, s84, v39
	s_or_b64 s[82:83], s[6:7], vcc
	v_writelane_b32 v243, s6, 28
	v_or_b32_e32 v38, 3, v38
	v_add_u32_e32 v64, s2, v50
	v_writelane_b32 v243, s7, 29
	v_add_u32_e32 v90, s2, v2
	s_mov_b32 s2, s4
	v_add_u32_e32 v2, s4, v2
	s_and_b64 s[80:81], s[80:81], s[82:83]
	v_cmp_gt_i32_e32 vcc, v38, v36
	v_cmp_le_i32_e64 s[82:83], v38, v37
	v_writelane_b32 v243, s2, 30
	v_or_b32_e32 v80, v2, v56
	v_lshlrev_b32_e32 v58, 3, v51
	v_mov_b64_e32 v[36:37], s[88:89]
	v_writelane_b32 v243, s3, 31
	v_mad_i64_i32 v[82:83], s[2:3], v80, s92, v[36:37]
	v_lshlrev_b32_e32 v2, 4, v51
	v_bitop3_b32 v60, v58, 8, v58 bitop3:0xc
	v_lshl_add_u64 v[36:37], v[82:83], 0, v[2:3]
	v_lshlrev_b32_e32 v44, 1, v60
	v_mov_b32_e32 v45, v3
	s_and_b64 s[82:83], vcc, s[82:83]
	v_cmp_lt_i32_e32 vcc, s84, v38
	global_load_dwordx4 v[40:43], v[36:37], off offset:2048
	s_nop 0
	global_load_dwordx4 v[36:39], v[36:37], off offset:2112
	v_lshl_add_u64 v[44:45], v[82:83], 0, v[44:45]
	global_load_dwordx4 v[44:47], v[44:45], off offset:2048
	v_mul_lo_u32 v59, v59, s93
	v_add_u32_e32 v59, s96, v59
	v_mul_u32_u24_e32 v100, 0x210, v56
	v_add3_u32 v109, v59, v100, v58
	v_mul_lo_u32 v59, v50, s97
	v_add_u32_e32 v62, 0, v59
	v_lshl_add_u32 v115, v55, 1, v62
	v_mad_u64_u32 v[62:63], s[2:3], v50, s98, v[62:63]
	v_lshl_add_u64 v[52:53], s[88:89], 0, v[52:53]
	s_mov_b32 s2, 0xfff70b80
	v_lshl_add_u64 v[52:53], v[48:49], 1, v[52:53]
	s_mov_b32 s3, -1
	v_lshl_add_u64 v[86:87], v[52:53], 0, s[2:3]
	s_mov_b32 s2, 0xfff70a80
	s_mov_b32 s3, -1
	v_max_i32_e32 v50, 0x80, v64
	v_lshl_add_u64 v[88:89], v[52:53], 0, s[2:3]
	v_or_b32_e32 v52, v90, v56
	v_lshl_add_u32 v64, v50, 4, v183
	v_lshlrev_b32_e32 v52, 4, v52
	s_or_b64 s[84:85], s[6:7], vcc
	v_ashrrev_i32_e32 v65, 31, v64
	v_ashrrev_i32_e32 v53, 31, v52
	s_and_b64 s[82:83], s[82:83], s[84:85]
	v_lshl_add_u64 v[84:85], v[64:65], 2, s[86:87]
	v_lshl_add_u64 v[90:91], v[52:53], 2, s[86:87]
	s_mov_b32 s2, s96
	v_readlane_b32 s84, v244, 10
	v_readlane_b32 s88, v244, 14
	v_readlane_b32 s89, v244, 15
	v_readlane_b32 s90, v244, 16
	v_readlane_b32 s91, v244, 17
	v_readlane_b32 s92, v244, 18
	v_readlane_b32 s93, v244, 19
	v_readlane_b32 s94, v244, 20
	v_readlane_b32 s95, v244, 21
	v_readlane_b32 s96, v244, 22
	v_readlane_b32 s97, v244, 23
	s_mov_b64 s[8:9], s[88:89]
	v_add_u32_e32 v52, 0, v2
	s_mov_b64 s[12:13], s[92:93]
	v_lshlrev_b32_e32 v2, 5, v51
	v_lshl_add_u64 v[94:95], s[12:13], 0, v[2:3]
	v_lshlrev_b32_e32 v2, 2, v60
	s_mov_b64 s[10:11], s[90:91]
	s_mov_b64 s[14:15], s[94:95]
	s_mov_b64 s[16:17], s[96:97]
	s_movk_i32 s97, 0x90
	v_add_u32_e32 v96, 0x21e00, v2
	v_or_b32_e32 v2, v68, v56
	v_lshlrev_b32_e32 v92, 2, v48
	v_add_u32_e32 v92, 0x21d00, v92
	v_mul_lo_u32 v48, v2, s97
	v_or_b32_e32 v2, v69, v56
	v_mul_lo_u32 v49, v2, s97
	v_or_b32_e32 v2, v71, v56
	v_mul_lo_u32 v55, v2, s97
	v_or_b32_e32 v2, v72, v56
	v_mul_lo_u32 v59, v2, s97
	v_or_b32_e32 v2, v74, v56
	v_mul_lo_u32 v61, v2, s97
	v_or_b32_e32 v2, v75, v56
	v_mul_lo_u32 v63, v2, s97
	v_or_b32_e32 v2, v77, v56
	v_mul_lo_u32 v64, v2, s97
	v_or_b32_e32 v2, v78, v56
	v_mul_lo_u32 v65, v2, s97
	v_or_b32_e32 v2, v98, v56
	v_lshlrev_b32_e32 v128, 2, v66
	v_mov_b32_e32 v53, v52
	v_mul_lo_u32 v66, v2, s97
	v_or_b32_e32 v2, v99, v56
	v_mul_u32_u24_e32 v50, 0x4200, v54
	v_lshlrev_b32_e32 v113, 2, v67
	v_readlane_b32 s85, v244, 11
	v_readlane_b32 s86, v244, 12
	v_readlane_b32 s87, v244, 13
	v_readlane_b32 s98, v244, 24
	v_mul_lo_u32 v56, v2, s97
	v_lshl_add_u32 v57, v57, 5, v53
	v_lshl_add_u32 v67, v70, 5, v53
	v_lshl_add_u32 v68, v73, 5, v53
	v_lshl_add_u32 v69, v76, 5, v53
	v_lshl_add_u32 v53, v79, 5, v53
	v_ashrrev_i32_e32 v81, 31, v80
	v_readlane_b32 s99, v244, 25
	s_movk_i32 s98, 0xff72
	s_mov_b32 s96, s2
	s_movk_i32 s93, 0x2100
	s_movk_i32 s92, 0x1200
	v_and_b32_e32 v241, 24, v62
	v_and_b32_e32 v242, 32, v62
	v_and_b32_e32 v62, 0xffffffc7, v62
	v_lshlrev_b32_e32 v241, 1, v241
	v_lshrrev_b32_e32 v242, 2, v242
	v_or3_b32 v62, v62, v241, v242
	v_add_u32_e32 v116, v62, v50
	v_lshlrev_b32_e32 v2, 1, v60
	v_lshlrev_b32_e32 v98, 1, v58
	v_add_u32_e32 v117, v52, v48
	v_add_u32_e32 v118, v52, v49
	v_add_u32_e32 v119, v52, v55
	v_add_u32_e32 v120, v52, v59
	v_add_u32_e32 v121, v52, v61
	v_add_u32_e32 v122, v52, v63
	v_add_u32_e32 v123, v52, v64
	v_add_u32_e32 v124, v52, v65
	v_add_u32_e32 v125, v52, v66
	v_add_u32_e32 v126, v52, v56
	v_add_u32_e32 v127, v57, v100
	v_add_u32_e32 v130, v67, v100
	v_add_u32_e32 v131, v68, v100
	v_add_u32_e32 v132, v69, v100
	v_add_u32_e32 v133, v53, v100
	v_cmp_eq_u32_e64 s[84:85], 0, v54
	v_cmp_gt_u32_e64 s[86:87], 2, v51
	global_load_dwordx4 v[224:227], v[94:95], off
	global_load_dwordx4 v[228:231], v[94:95], off offset:16
	global_load_dwordx4 v[232:235], v[94:95], off offset:128
	global_load_dwordx4 v[236:239], v[94:95], off offset:144
	global_load_dwordx4 v[248:251], v[90:91], off offset:32
	global_load_dwordx4 v[252:255], v[90:91], off offset:48
	v_mov_b32_e32 v240, 1.0
	v_mov_b32_e32 v241, 1.0
	v_mov_b32_e32 v242, 1.0
	v_mov_b32_e32 v245, 1.0
	v_mov_b32_e32 v246, 1.0
	v_mov_b32_e32 v247, 1.0
	v_mov_b32_e32 v217, 1.0
	v_mov_b32_e32 v219, 1.0
	s_and_saveexec_b64 vcc, s[86:87]
	global_load_dword v240, v[90:91], off
	global_load_dword v241, v[90:91], off offset:4
	global_load_dword v242, v[90:91], off offset:8
	global_load_dword v245, v[90:91], off offset:12
	global_load_dword v246, v[90:91], off offset:16
	global_load_dword v247, v[90:91], off offset:20
	global_load_dword v217, v[90:91], off offset:24
	global_load_dword v219, v[90:91], off offset:28
	s_or_b64 exec, exec, vcc
	s_waitcnt vmcnt(17)
	v_and_b32_e32 v90, 63, v0
	v_lshlrev_b32_e32 v90, 2, v90
	v_add_u32_e32 v90, 0x21d00, v90
	ds_write_b32 v90, v129
	ds_write_b32 v90, v223 offset:256
	s_waitcnt lgkmcnt(0)
	v_readlane_b32 s8, v244, 22
	v_readlane_b32 s9, v244, 23
	s_nop 4
	s_load_dwordx4 s[4:7], s[8:9], 0x0
	s_waitcnt lgkmcnt(0)
	v_writelane_b32 v243, s4, 36
	v_writelane_b32 v243, s5, 37
	v_writelane_b32 v243, s6, 38
	v_writelane_b32 v243, s7, 39
	s_mov_b64 s[2:3], -1
	s_branch .LBB0_182

.LBB0_188:
	ds_read_b32 v79, v96
	ds_read2_b32 v[64:65], v96 offset0:1 offset1:2
	ds_read2_b32 v[66:67], v96 offset0:3 offset1:4
	ds_read2_b32 v[76:77], v96 offset0:5 offset1:6
	ds_read_b32 v78, v96 offset:28
	s_xor_b64 s[88:89], s[2:3], -1
	s_mov_b32 s90, 0
	s_mov_b64 s[2:3], -1
	v_mul_f32_e32 v102, v114, v248
	v_mul_f32_e32 v103, v114, v249
	v_mul_f32_e32 v104, v114, v250
	v_mul_f32_e32 v105, v114, v251
	v_mul_f32_e32 v106, v114, v252
	v_mul_f32_e32 v107, v114, v253
	v_mul_f32_e32 v108, v114, v254
	v_mul_f32_e32 v101, v114, v255
	s_branch .LBB0_190
.LBB0_189:
	v_readlane_b32 s4, v244, 10
	s_xor_b64 s[2:3], s[2:3], -1
	s_lshl_b64 s[94:95], s[90:91], 2
	v_readlane_b32 s16, v244, 22
	v_readlane_b32 s17, v244, 23
	s_add_u32 s94, s16, s94
	s_addc_u32 s95, s17, s95
	ds_read_b128 v[134:137], v117
	ds_read_b128 v[138:141], v117 offset:64
	s_add_i32 s94, s90, 36
	v_readlane_b32 s94, v243, s94
	ds_read_b128 v[142:145], v118
	ds_read_b128 v[146:149], v118 offset:64
	s_waitcnt lgkmcnt(3)
	v_mfma_f32_16x16x32_bf16 v[134:137], v[134:137], v[72:75], 0
	v_readlane_b32 s6, v244, 12
	v_readlane_b32 s7, v244, 13
	s_mov_b32 s4, 0xf149f2ca
	s_waitcnt lgkmcnt(1)
	v_mfma_f32_16x16x32_bf16 v[142:145], v[142:145], v[72:75], 0
	v_readlane_b32 s6, v243, 12
	v_mov_b32_e32 v100, s4
	v_readlane_b32 s7, v243, 13
	v_mfma_f32_16x16x32_bf16 v[134:137], v[138:141], v[68:71], v[134:137]
	ds_read_b128 v[138:141], v119
	v_mov_b32_e32 v178, s4
	v_mov_b32_e32 v216, s4
	s_waitcnt lgkmcnt(1)
	v_mfma_f32_16x16x32_bf16 v[142:145], v[146:149], v[68:71], v[142:145]
	ds_read_b128 v[146:149], v119 offset:64
	ds_read_b128 v[150:153], v120
	ds_read_b128 v[154:157], v120 offset:64
	ds_read_b128 v[158:161], v121
	ds_read_b128 v[162:165], v121 offset:64
	v_cndmask_b32_e64 v100, v100, v134, s[6:7]
	s_waitcnt lgkmcnt(5)
	v_mfma_f32_16x16x32_bf16 v[138:141], v[138:141], v[72:75], 0
	v_readlane_b32 s6, v243, 14
	v_readlane_b32 s7, v243, 15
	v_mov_b32_e32 v218, s4
	s_waitcnt lgkmcnt(1)
	v_mfma_f32_16x16x32_bf16 v[158:161], v[158:161], v[72:75], 0
	v_mov_b32_e32 v220, s4
	v_mov_b32_e32 v222, s4
	v_readlane_b32 s5, v244, 11
	v_mfma_f32_16x16x32_bf16 v[138:141], v[146:149], v[68:71], v[138:141]
	ds_read_b128 v[146:149], v122
	ds_read_b128 v[166:169], v122 offset:64
	ds_read_b128 v[170:173], v123
	ds_read_b128 v[174:177], v123 offset:64
	ds_read_b128 v[196:199], v124
	ds_read_b128 v[200:203], v124 offset:64
	ds_read_b128 v[204:207], v125
	ds_read_b128 v[208:211], v125 offset:64
	v_readlane_b32 s8, v244, 14
	s_waitcnt lgkmcnt(8)
	v_mfma_f32_16x16x32_bf16 v[158:161], v[162:165], v[68:71], v[158:161]
	v_cndmask_b32_e64 v163, v184, v135, s[6:7]
	v_readlane_b32 s6, v243, 16
	v_readlane_b32 s7, v243, 17
	s_waitcnt lgkmcnt(7)
	v_mfma_f32_16x16x32_bf16 v[146:149], v[146:149], v[72:75], 0
	v_mov_b32_e32 v162, s4
	v_cndmask_b32_e64 v165, v184, v136, s[6:7]
	v_readlane_b32 s6, v243, 18
	v_readlane_b32 s7, v243, 19
	s_waitcnt lgkmcnt(6)
	v_mfma_f32_16x16x32_bf16 v[146:149], v[166:169], v[68:71], v[146:149]
	v_cndmask_b32_e64 v158, v162, v158, s[36:37]
	v_cndmask_b32_e64 v166, v184, v137, s[6:7]
	v_readlane_b32 s6, v243, 20
	v_readlane_b32 s7, v243, 21
	v_mfma_f32_16x16x32_bf16 v[150:153], v[150:153], v[72:75], 0
	v_cndmask_b32_e64 v159, v184, v159, s[38:39]
	v_cndmask_b32_e64 v167, v178, v142, s[6:7]
	v_readlane_b32 s6, v243, 22
	v_readlane_b32 s7, v243, 23
	v_mfma_f32_16x16x32_bf16 v[150:153], v[154:157], v[68:71], v[150:153]
	ds_read_b128 v[154:157], v126
	ds_read_b128 v[212:215], v126 offset:64
	v_cndmask_b32_e64 v168, v184, v143, s[6:7]
	v_readlane_b32 s6, v243, 24
	v_readlane_b32 s7, v243, 25
	s_waitcnt lgkmcnt(7)
	v_mfma_f32_16x16x32_bf16 v[134:137], v[170:173], v[72:75], 0
	v_cndmask_b32_e64 v171, v216, v138, s[0:1]
	v_cndmask_b32_e64 v169, v184, v144, s[6:7]
	v_readlane_b32 s6, v243, 26
	v_readlane_b32 s7, v243, 27
	s_waitcnt lgkmcnt(6)
	v_mfma_f32_16x16x32_bf16 v[134:137], v[174:177], v[68:71], v[134:137]
	v_cndmask_b32_e64 v172, v184, v139, s[20:21]
	v_cndmask_b32_e64 v170, v184, v145, s[6:7]
	v_cndmask_b32_e64 v173, v184, v140, s[22:23]
	s_waitcnt lgkmcnt(5)
	v_mfma_f32_16x16x32_bf16 v[142:145], v[196:199], v[72:75], 0
	v_cndmask_b32_e64 v174, v184, v141, s[24:25]
	v_cndmask_b32_e64 v150, v218, v150, s[26:27]
	v_cndmask_b32_e64 v151, v184, v151, s[28:29]
	s_waitcnt lgkmcnt(4)
	v_mfma_f32_16x16x32_bf16 v[138:141], v[200:203], v[68:71], v[142:145]
	v_cndmask_b32_e64 v152, v184, v152, s[30:31]
	v_cndmask_b32_e64 v153, v184, v153, s[34:35]
	v_mov_b32_e32 v164, s4
	s_waitcnt lgkmcnt(3)
	v_mfma_f32_16x16x32_bf16 v[142:145], v[204:207], v[72:75], 0
	v_cndmask_b32_e64 v160, v184, v160, s[40:41]
	v_cndmask_b32_e64 v161, v184, v161, s[42:43]
	v_cndmask_b32_e64 v146, v164, v146, s[44:45]
	s_waitcnt lgkmcnt(1)
	v_mfma_f32_16x16x32_bf16 v[72:75], v[154:157], v[72:75], 0
	v_cndmask_b32_e64 v147, v184, v147, s[46:47]
	v_cndmask_b32_e64 v148, v184, v148, s[48:49]
	v_cndmask_b32_e64 v149, v184, v149, s[50:51]
	v_mfma_f32_16x16x32_bf16 v[142:145], v[208:211], v[68:71], v[142:145]
	v_cndmask_b32_e64 v134, v220, v134, s[52:53]
	v_cndmask_b32_e64 v135, v184, v135, s[54:55]
	v_readlane_b32 s9, v244, 15
	s_waitcnt lgkmcnt(0)
	v_mfma_f32_16x16x32_bf16 v[68:71], v[212:215], v[68:71], v[72:75]
	v_readlane_b32 s10, v244, 16
	s_nop 1
	v_cndmask_b32_e64 v154, v184, v143, s[70:71]
	v_cndmask_b32_e64 v155, v184, v144, s[72:73]
	v_mov_b32_e32 v99, s94
	v_mul_f32_e32 v72, 0x3fb8aa3b, v99
	v_max3_f32 v72, v72, v100, v163
	v_max3_f32 v72, v72, v165, v166
	v_max3_f32 v72, v72, v167, v168
	v_max3_f32 v72, v72, v169, v170
	v_max3_f32 v72, v72, v171, v172
	v_max3_f32 v72, v72, v173, v174
	v_max3_f32 v72, v72, v150, v151
	v_max3_f32 v72, v72, v152, v153
	v_max3_f32 v72, v72, v158, v159
	v_max3_f32 v72, v72, v160, v161
	v_max3_f32 v72, v72, v146, v147
	v_max3_f32 v72, v72, v148, v149
	v_cndmask_b32_e64 v73, v184, v136, s[56:57]
	v_cndmask_b32_e64 v74, v184, v137, s[58:59]
	v_max3_f32 v72, v72, v134, v135
	v_cndmask_b32_e64 v75, v222, v138, s[60:61]
	v_cndmask_b32_e64 v136, v184, v139, s[62:63]
	v_max3_f32 v72, v72, v73, v74
	v_max3_f32 v72, v72, v75, v136
	v_cndmask_b32_e64 v137, v184, v140, s[64:65]
	v_cndmask_b32_e64 v138, v184, v141, s[66:67]
	v_max3_f32 v139, v72, v137, v138
	v_mov_b32_e32 v72, s4
	v_cndmask_b32_e64 v140, v72, v142, s[68:69]
	v_max3_f32 v72, v139, v140, v154
	v_cndmask_b32_e64 v162, v184, v145, s[74:75]
	v_max3_f32 v139, v72, v155, v162
	v_mov_b32_e32 v72, s4
	v_cndmask_b32_e64 v164, v72, v68, s[76:77]
	v_cndmask_b32_e64 v175, v184, v69, s[78:79]
	v_max3_f32 v68, v139, v164, v175
	v_cndmask_b32_e64 v176, v184, v70, s[80:81]
	v_cndmask_b32_e64 v177, v184, v71, s[82:83]
	v_max3_f32 v68, v68, v176, v177
	v_mov_b32_e32 v69, v68
	s_nop 1
	v_permlane16_swap_b32 v69, v68
	s_mov_b32 s4, 0x3fb8aa3b
	v_readlane_b32 s11, v244, 17
	v_readlane_b32 s12, v244, 18
	v_readlane_b32 s13, v244, 19
	s_waitcnt lgkmcnt(0)
	v_max_f32_e32 v69, v69, v69
	v_max_f32_e32 v68, v68, v69
	v_mov_b32_e32 v69, v68
	s_nop 1
	v_permlane32_swap_b32 v69, v68
	v_readlane_b32 s14, v244, 20
	v_readlane_b32 s15, v244, 21
	v_readlane_b32 s18, v244, 24
	v_readlane_b32 s19, v244, 25
	s_waitcnt lgkmcnt(0)
	v_max_f32_e32 v69, v69, v69
	v_max_f32_e32 v178, v68, v69
	v_sub_f32_e32 v68, v100, v178
	v_exp_f32_e32 v72, v68
	v_sub_f32_e32 v68, v163, v178
	v_exp_f32_e32 v100, v68
	v_sub_f32_e32 v69, v165, v178
	v_exp_f32_e32 v139, v69
	v_sub_f32_e32 v69, v166, v178
	v_exp_f32_e32 v141, v69
	v_sub_f32_e32 v69, v167, v178
	v_add_f32_e32 v68, 0, v72
	v_exp_f32_e32 v142, v69
	v_sub_f32_e32 v69, v168, v178
	v_add_f32_e32 v68, v100, v68
	v_exp_f32_e32 v143, v69
	v_sub_f32_e32 v69, v169, v178
	v_add_f32_e32 v68, v139, v68
	v_exp_f32_e32 v144, v69
	v_sub_f32_e32 v69, v170, v178
	v_add_f32_e32 v68, v141, v68
	v_exp_f32_e32 v145, v69
	v_sub_f32_e32 v69, v171, v178
	v_add_f32_e32 v68, v142, v68
	v_exp_f32_e32 v156, v69
	v_sub_f32_e32 v69, v172, v178
	v_add_f32_e32 v68, v143, v68
	v_exp_f32_e32 v157, v69
	v_sub_f32_e32 v69, v173, v178
	v_add_f32_e32 v68, v144, v68
	v_exp_f32_e32 v163, v69
	v_sub_f32_e32 v69, v174, v178
	v_add_f32_e32 v68, v145, v68
	v_exp_f32_e32 v165, v69
	v_sub_f32_e32 v69, v150, v178
	v_add_f32_e32 v68, v156, v68
	v_exp_f32_e32 v166, v69
	v_sub_f32_e32 v69, v151, v178
	v_add_f32_e32 v68, v157, v68
	v_exp_f32_e32 v167, v69
	v_sub_f32_e32 v69, v152, v178
	v_add_f32_e32 v68, v163, v68
	v_exp_f32_e32 v168, v69
	v_sub_f32_e32 v69, v153, v178
	v_add_f32_e32 v68, v165, v68
	v_exp_f32_e32 v169, v69
	v_sub_f32_e32 v69, v158, v178
	v_add_f32_e32 v68, v166, v68
	v_exp_f32_e32 v158, v69
	v_sub_f32_e32 v69, v159, v178
	v_add_f32_e32 v68, v167, v68
	v_exp_f32_e32 v159, v69
	v_sub_f32_e32 v69, v160, v178
	v_add_f32_e32 v68, v168, v68
	v_exp_f32_e32 v160, v69
	v_sub_f32_e32 v69, v161, v178
	v_add_f32_e32 v68, v169, v68
	v_exp_f32_e32 v161, v69
	v_sub_f32_e32 v69, v146, v178
	v_add_f32_e32 v68, v158, v68
	v_exp_f32_e32 v170, v69
	v_sub_f32_e32 v69, v147, v178
	v_add_f32_e32 v68, v159, v68
	v_exp_f32_e32 v171, v69
	v_sub_f32_e32 v69, v148, v178
	v_add_f32_e32 v68, v160, v68
	v_exp_f32_e32 v172, v69
	v_sub_f32_e32 v69, v149, v178
	v_add_f32_e32 v68, v161, v68
	v_exp_f32_e32 v173, v69
	v_sub_f32_e32 v69, v134, v178
	v_add_f32_e32 v68, v170, v68
	v_exp_f32_e32 v174, v69
	v_sub_f32_e32 v69, v135, v178
	v_add_f32_e32 v68, v171, v68
	v_exp_f32_e32 v179, v69
	v_sub_f32_e32 v69, v73, v178
	v_add_f32_e32 v68, v172, v68
	v_exp_f32_e32 v195, v69
	v_sub_f32_e32 v69, v74, v178
	v_add_f32_e32 v68, v173, v68
	v_exp_f32_e32 v196, v69
	v_sub_f32_e32 v69, v75, v178
	v_add_f32_e32 v68, v174, v68
	v_exp_f32_e32 v197, v69
	v_sub_f32_e32 v69, v136, v178
	v_add_f32_e32 v68, v179, v68
	v_exp_f32_e32 v198, v69
	v_add_f32_e32 v68, v195, v68
	v_add_f32_e32 v68, v196, v68
	v_add_f32_e32 v68, v197, v68
	v_add_f32_e32 v146, v198, v68
	v_sub_f32_e32 v68, v137, v178
	v_exp_f32_e32 v199, v68
	v_sub_f32_e32 v68, v138, v178
	v_add_u32_e32 v74, 0xb000, v127
	v_exp_f32_e32 v200, v68
	v_add_u32_e32 v68, 0x9000, v127
	v_cvt_pk_bf16_f32 v72, v72, v100
	ds_read_b128 v[134:137], v74 offset:256
	v_cvt_pk_bf16_f32 v74, v142, v143
	v_add_u32_e32 v100, 0xd000, v127
	v_add_u32_e32 v142, 0xf000, v127
	v_sub_f32_e32 v147, v140, v178
	ds_read_b128 v[68:71], v68
	v_cvt_pk_bf16_f32 v73, v139, v141
	v_cvt_pk_bf16_f32 v75, v144, v145
	ds_read_b128 v[138:141], v100 offset:512
	ds_read_b128 v[142:145], v142 offset:768
	s_waitcnt lgkmcnt(2)
	v_mfma_f32_16x16x32_bf16 v[68:71], v[68:71], v[72:75], 0
	v_exp_f32_e32 v100, v147
	v_add_f32_e32 v146, v199, v146
	v_add_f32_e32 v146, v200, v146
	v_mfma_f32_16x16x32_bf16 v[134:137], v[134:137], v[72:75], 0
	v_add_f32_e32 v201, v100, v146
	v_sub_f32_e32 v146, v154, v178
	v_add_u32_e32 v148, 0xb000, v130
	s_waitcnt lgkmcnt(1)
	v_mfma_f32_16x16x32_bf16 v[138:141], v[138:141], v[72:75], 0
	v_exp_f32_e32 v202, v146
	v_cvt_pk_bf16_f32 v146, v156, v157
	v_cvt_pk_bf16_f32 v147, v163, v165
	s_waitcnt lgkmcnt(0)
	v_mfma_f32_16x16x32_bf16 v[72:75], v[142:145], v[72:75], 0
	v_add_u32_e32 v142, 0x9000, v130
	ds_read_b128 v[142:145], v142
	ds_read_b128 v[150:153], v148 offset:256
	v_cvt_pk_bf16_f32 v148, v166, v167
	v_cvt_pk_bf16_f32 v149, v168, v169
	v_add_u32_e32 v154, 0xd000, v130
	s_waitcnt lgkmcnt(1)
	v_mfma_f32_16x16x32_bf16 v[68:71], v[142:145], v[146:149], v[68:71]
	v_add_u32_e32 v142, 0xf000, v130
	ds_read_b128 v[142:145], v142 offset:768
	v_sub_f32_e32 v203, v155, v178
	ds_read_b128 v[154:157], v154 offset:512
	s_waitcnt lgkmcnt(1)
	v_mfma_f32_16x16x32_bf16 v[72:75], v[142:145], v[146:149], v[72:75]
	v_add_u32_e32 v142, 0x9000, v131
	ds_read_b128 v[142:145], v142
	v_exp_f32_e32 v163, v203
	v_mfma_f32_16x16x32_bf16 v[134:137], v[150:153], v[146:149], v[134:137]
	v_sub_f32_e32 v150, v162, v178
	v_exp_f32_e32 v162, v150
	v_add_f32_e32 v150, v202, v201
	s_waitcnt lgkmcnt(1)
	v_mfma_f32_16x16x32_bf16 v[138:141], v[154:157], v[146:149], v[138:141]
	v_add_f32_e32 v150, v163, v150
	v_add_u32_e32 v148, 0xb000, v131
	v_add_f32_e32 v165, v162, v150
	v_cvt_pk_bf16_f32 v146, v158, v159
	v_cvt_pk_bf16_f32 v147, v160, v161
	ds_read_b128 v[150:153], v148 offset:256
	v_cvt_pk_bf16_f32 v148, v170, v171
	v_cvt_pk_bf16_f32 v149, v172, v173
	v_add_u32_e32 v154, 0xd000, v131
	s_waitcnt lgkmcnt(1)
	v_mfma_f32_16x16x32_bf16 v[68:71], v[142:145], v[146:149], v[68:71]
	v_add_u32_e32 v142, 0xf000, v131
	ds_read_b128 v[142:145], v142 offset:768
	ds_read_b128 v[154:157], v154 offset:512
	s_waitcnt lgkmcnt(1)
	v_mfma_f32_16x16x32_bf16 v[72:75], v[142:145], v[146:149], v[72:75]
	v_add_u32_e32 v142, 0x9000, v132
	ds_read_b128 v[142:145], v142
	v_sub_f32_e32 v164, v164, v178
	v_mfma_f32_16x16x32_bf16 v[134:137], v[150:153], v[146:149], v[134:137]
	v_sub_f32_e32 v150, v175, v178
	v_exp_f32_e32 v160, v150
	v_sub_f32_e32 v150, v176, v178
	s_waitcnt lgkmcnt(1)
	v_mfma_f32_16x16x32_bf16 v[138:141], v[154:157], v[146:149], v[138:141]
	v_add_u32_e32 v148, 0xb000, v132
	v_exp_f32_e32 v161, v150
	ds_read_b128 v[150:153], v148 offset:256
	v_exp_f32_e32 v158, v164
	v_sub_f32_e32 v164, v177, v178
	v_exp_f32_e32 v164, v164
	v_cvt_pk_bf16_f32 v146, v174, v179
	v_add_f32_e32 v159, v158, v165
	v_cvt_pk_bf16_f32 v147, v195, v196
	v_cvt_pk_bf16_f32 v148, v197, v198
	v_cvt_pk_bf16_f32 v149, v199, v200
	v_add_u32_e32 v154, 0xd000, v132
	s_waitcnt lgkmcnt(1)
	v_mfma_f32_16x16x32_bf16 v[68:71], v[142:145], v[146:149], v[68:71]
	v_add_f32_e32 v142, v160, v159
	v_add_f32_e32 v142, v161, v142
	ds_read_b128 v[154:157], v154 offset:512
	s_waitcnt lgkmcnt(1)
	v_mfma_f32_16x16x32_bf16 v[134:137], v[150:153], v[146:149], v[134:137]
	v_add_f32_e32 v150, v164, v142
	v_add_u32_e32 v142, 0xf000, v132
	ds_read_b128 v[142:145], v142 offset:768
	ds_bpermute_b32 v151, v128, v150
	s_waitcnt lgkmcnt(1)
	v_mfma_f32_16x16x32_bf16 v[72:75], v[142:145], v[146:149], v[72:75]
	v_add_u32_e32 v142, 0x9000, v133
	ds_read_b128 v[142:145], v142
	s_waitcnt lgkmcnt(1)
	v_add_f32_e32 v159, v150, v151
	v_mfma_f32_16x16x32_bf16 v[138:141], v[154:157], v[146:149], v[138:141]
	ds_bpermute_b32 v165, v113, v159
	v_cvt_pk_bf16_f32 v146, v100, v202
	v_add_u32_e32 v100, 0xb000, v133
	ds_read_b128 v[150:153], v100 offset:256
	v_add_u32_e32 v100, 0xd000, v133
	v_fma_f32 v99, v99, s4, -v178
	ds_read_b128 v[154:157], v100 offset:512
	v_add_u32_e32 v100, 0xf000, v133
	v_exp_f32_e32 v99, v99
	v_cvt_pk_bf16_f32 v147, v163, v162
	v_cvt_pk_bf16_f32 v148, v158, v160
	v_cvt_pk_bf16_f32 v149, v161, v164
	v_writelane_b32 v244, s90, 62
	s_waitcnt lgkmcnt(3)
	v_mfma_f32_16x16x32_bf16 v[68:71], v[142:145], v[146:149], v[68:71]
	ds_read_b128 v[142:145], v100 offset:768
	s_waitcnt lgkmcnt(3)
	v_add_f32_e32 v100, v159, v165
	v_add_f32_e32 v99, v99, v100
	v_rcp_f32_e32 v100, v99
	s_waitcnt lgkmcnt(2)
	v_mfma_f32_16x16x32_bf16 v[134:137], v[150:153], v[146:149], v[134:137]
	v_lshl_add_u32 v99, s90, 7, v109
	s_mov_b32 s16, 0xf149f2ca
	v_pk_mul_f32 v[70:71], v[70:71], v[100:101] op_sel_hi:[1,0]
	s_waitcnt lgkmcnt(1)
	v_mfma_f32_16x16x32_bf16 v[138:141], v[154:157], v[146:149], v[138:141]
	v_mul_f32_e64 v68, v68, v100
	v_mul_f32_e64 v69, v69, v100
	s_nop 0
	v_pk_mul_f32 v[134:135], v[134:135], v[100:101] op_sel_hi:[1,0]
	v_writelane_b32 v244, s91, 63
	s_waitcnt lgkmcnt(0)
	v_mfma_f32_16x16x32_bf16 v[72:75], v[142:145], v[146:149], v[72:75]
	v_mul_f32_e64 v142, v70, v70
	v_mul_f32_e64 v143, v71, v71
	v_pk_mul_f32 v[144:145], v[68:69], v[68:69]
	v_cvt_pk_bf16_f32 v68, v68, v69
	v_cvt_pk_bf16_f32 v69, v70, v71
	v_pk_mul_f32 v[70:71], v[136:137], v[100:101] op_sel_hi:[1,0]
	v_pk_mov_b32 v[146:147], v[144:145], v[142:143] op_sel:[1,0]
	v_mov_b32_e32 v145, v143
	v_pk_add_f32 v[142:143], v[146:147], v[144:145]
	v_pk_mul_f32 v[136:137], v[70:71], v[70:71]
	v_add_f32_e32 v142, v142, v143
	v_pk_mul_f32 v[144:145], v[134:135], v[134:135]
	v_cvt_pk_bf16_f32 v134, v134, v135
	v_cvt_pk_bf16_f32 v135, v70, v71
	v_pk_mul_f32 v[70:71], v[138:139], v[100:101] op_sel_hi:[1,0]
	v_add_f32_e32 v143, v110, v142
	v_pk_mov_b32 v[146:147], v[144:145], v[136:137] op_sel:[1,0]
	v_mov_b32_e32 v145, v137
	ds_write2_b64 v99, v[68:69], v[134:135] offset1:4
	v_pk_mul_f32 v[68:69], v[140:141], v[100:101] op_sel_hi:[1,0]
	v_mul_f32_e32 v110, v70, v70
	v_pk_add_f32 v[136:137], v[146:147], v[144:145]
	v_pk_fma_f32 v[134:135], v[70:71], v[70:71], v[110:111] op_sel_hi:[1,1,0]
	v_mul_f32_e32 v110, v68, v68
	v_pk_add_f32 v[136:137], v[136:137], v[136:137] op_sel_hi:[0,1]
	v_pk_fma_f32 v[138:139], v[68:69], v[68:69], v[110:111] op_sel_hi:[1,1,0]
	v_cvt_pk_bf16_f32 v70, v70, v71
	v_cvt_pk_bf16_f32 v71, v68, v69
	v_pk_mul_f32 v[68:69], v[74:75], v[100:101] op_sel_hi:[1,0]
	v_pk_mul_f32 v[72:73], v[72:73], v[100:101] op_sel_hi:[1,0]
	v_mul_f32_e32 v136, v68, v68
	v_mul_f32_e32 v134, v72, v72
	v_mul_f32_e32 v138, v73, v73
	v_mul_f32_e32 v142, v69, v69
	v_pk_add_f32 v[74:75], v[134:135], v[138:139]
	v_pk_add_f32 v[134:135], v[136:137], v[142:143]
	s_and_b64 vcc, exec, s[2:3]
	v_pk_add_f32 v[74:75], v[74:75], v[134:135]
	s_mov_b32 s90, 1
	v_add_f32_e32 v110, v74, v75
	s_mov_b64 s[2:3], 0
	v_cvt_pk_bf16_f32 v72, v72, v73
	v_cvt_pk_bf16_f32 v73, v68, v69
	ds_write2_b64 v99, v[70:71], v[72:73] offset0:8 offset1:12
	s_cbranch_vccnz .LBB0_181
.LBB0_190:
	s_cmp_eq_u32 s90, 0
	s_cbranch_scc1 .Lswa_qnw
	s_waitcnt vmcnt(0)
.Lswa_qnw:
	v_lshlrev_b32_e32 v100, 16, v36
	v_and_b32_e32 v99, 0xffff0000, v36
	v_lshlrev_b32_e32 v134, 16, v40
	v_and_b32_e32 v135, 0xffff0000, v40
	v_mul_f32_e32 v68, v100, v100
	v_mul_f32_e32 v140, v99, v99
	v_lshlrev_b32_e32 v75, 16, v37
	v_fmac_f32_e32 v68, v134, v134
	v_fmac_f32_e32 v140, v135, v135
	v_lshlrev_b32_e32 v136, 16, v41
	v_add_f32_e32 v68, v68, v140
	v_mul_f32_e32 v140, v75, v75
	v_and_b32_e32 v74, 0xffff0000, v37
	v_fmac_f32_e32 v140, v136, v136
	v_and_b32_e32 v137, 0xffff0000, v41
	v_add_f32_e32 v68, v140, v68
	v_mul_f32_e32 v140, v74, v74
	v_lshlrev_b32_e32 v73, 16, v38
	v_fmac_f32_e32 v140, v137, v137
	v_lshlrev_b32_e32 v138, 16, v42
	v_add_f32_e32 v68, v140, v68
	v_mul_f32_e32 v140, v73, v73
	v_and_b32_e32 v72, 0xffff0000, v38
	v_fmac_f32_e32 v140, v138, v138
	v_and_b32_e32 v139, 0xffff0000, v42
	v_add_f32_e32 v68, v140, v68
	v_mul_f32_e32 v140, v72, v72
	v_lshlrev_b32_e32 v71, 16, v39
	v_fmac_f32_e32 v140, v139, v139
	v_lshlrev_b32_e32 v142, 16, v43
	v_add_f32_e32 v68, v140, v68
	v_mul_f32_e32 v140, v71, v71
	v_and_b32_e32 v70, 0xffff0000, v39
	v_fmac_f32_e32 v140, v142, v142
	v_and_b32_e32 v69, 0xffff0000, v43
	v_add_f32_e32 v68, v140, v68
	v_mul_f32_e32 v140, v70, v70
	v_fmac_f32_e32 v140, v69, v69
	v_add_f32_e32 v68, v140, v68
	v_mov_b32_e32 v140, v68
	s_nop 1
	v_permlane16_swap_b32 v140, v68
	v_mov_b32_e32 v141, v241
	s_waitcnt lgkmcnt(0)
	v_add_f32_e32 v145, v68, v140
	v_mov_b32_e32 v146, v145
	s_nop 1
	v_permlane32_swap_b32 v146, v145
	v_mov_b32_e32 v140, v240
	v_mov_b32_e32 v143, v242
	v_mov_b32_e32 v144, v245
	v_mov_b32_e32 v147, v246
	v_mov_b32_e32 v148, v247
	v_mov_b32_e32 v149, v217
	v_mov_b32_e32 v68, v219
	s_waitcnt lgkmcnt(0)
	v_add_f32_e32 v145, v145, v146
	v_fmamk_f32 v145, v145, 0x3c800000, v180
	v_rsq_f32_e32 v145, v145
	v_lshlrev_b32_e32 v146, 16, v47
	v_readlane_b32 s4, v244, 62
	v_readlane_b32 s5, v244, 63
	v_mul_f32_e32 v145, 0x3e38aa3b, v145
	v_mul_f32_e32 v146, v145, v146
	v_mul_f32_e32 v142, v145, v142
	s_waitcnt lgkmcnt(0)
	v_mul_f32_e32 v146, v146, v77
	v_mul_f32_e32 v142, v230, v142
	v_mul_f32_e32 v146, v108, v146
	v_fmac_f32_e32 v146, v142, v149
	v_and_b32_e32 v142, 0xffff0000, v46
	v_mul_f32_e32 v142, v145, v142
	v_mul_f32_e32 v139, v145, v139
	v_mul_f32_e32 v142, v142, v76
	v_mul_f32_e32 v139, v229, v139
	v_mul_f32_e32 v142, v107, v142
	v_fmac_f32_e32 v142, v139, v148
	v_lshlrev_b32_e32 v139, 16, v46
	v_mul_f32_e32 v139, v145, v139
	v_mul_f32_e32 v138, v145, v138
	v_mul_f32_e32 v139, v139, v67
	v_mul_f32_e32 v138, v228, v138
	v_mul_f32_e32 v139, v106, v139
	v_fmac_f32_e32 v139, v138, v147
	v_and_b32_e32 v138, 0xffff0000, v45
	v_mul_f32_e32 v138, v145, v138
	v_mul_f32_e32 v137, v145, v137
	v_mul_f32_e32 v138, v138, v66
	v_mul_f32_e32 v137, v227, v137
	v_mul_f32_e32 v138, v105, v138
	v_fmac_f32_e32 v138, v137, v144
	v_lshlrev_b32_e32 v137, 16, v45
	v_mul_f32_e32 v137, v145, v137
	v_mul_f32_e32 v136, v145, v136
	v_mul_f32_e32 v137, v137, v65
	v_mul_f32_e32 v136, v226, v136
	v_mul_f32_e32 v137, v104, v137
	v_fmac_f32_e32 v137, v136, v143
	v_and_b32_e32 v136, 0xffff0000, v44
	v_mul_f32_e32 v136, v145, v136
	v_mul_f32_e32 v135, v145, v135
	v_mul_f32_e32 v136, v136, v64
	v_mul_f32_e32 v135, v225, v135
	v_mul_f32_e32 v136, v103, v136
	v_fmac_f32_e32 v136, v135, v141
	v_lshlrev_b32_e32 v135, 16, v44
	v_mul_f32_e32 v135, v145, v135
	v_mul_f32_e32 v134, v145, v134
	v_mul_f32_e32 v135, v135, v79
	v_mul_f32_e32 v134, v224, v134
	v_mul_f32_e32 v135, v102, v135
	v_mul_f32_e32 v100, v145, v100
	v_mul_f32_e32 v69, v145, v69
	v_fmac_f32_e32 v135, v134, v140
	v_mul_f32_e32 v134, v232, v100
	v_mul_f32_e32 v100, v231, v69
	v_mul_f32_e32 v69, v145, v70
	v_mul_f32_e32 v147, v239, v69
	v_and_b32_e32 v69, 0xffff0000, v47
	v_mul_f32_e32 v69, v145, v69
	v_mul_f32_e32 v69, v69, v78
	v_mul_f32_e32 v71, v145, v71
	v_pk_mul_f32 v[68:69], v[100:101], v[68:69]
	s_or_b32 s90, s90, s33
	v_mul_f32_e32 v99, v145, v99
	v_mul_f32_e32 v75, v145, v75
	v_mul_f32_e32 v74, v145, v74
	v_mul_f32_e32 v73, v145, v73
	v_mul_f32_e32 v72, v145, v72
	v_mul_f32_e32 v71, v238, v71
	v_add_f32_e32 v68, v68, v69
	s_mov_b32 s91, s5
	s_cmp_eq_u32 s90, 3
	v_mul_f32_e32 v99, v233, v99
	v_mul_f32_e32 v140, v234, v75
	v_mul_f32_e32 v141, v235, v74
	v_mul_f32_e32 v143, v236, v73
	v_mul_f32_e32 v144, v237, v72
	v_cvt_pk_bf16_f32 v72, v135, v136
	v_cvt_pk_bf16_f32 v73, v137, v138
	v_cvt_pk_bf16_f32 v74, v139, v142
	v_cvt_pk_bf16_f32 v75, v146, v68
	v_cvt_pk_bf16_f32 v68, v134, v99
	v_cvt_pk_bf16_f32 v69, v140, v141
	v_cvt_pk_bf16_f32 v70, v143, v144
	v_cvt_pk_bf16_f32 v71, v71, v147
	s_cbranch_scc1 .LBB0_189
	s_lshl_b32 s94, s90, 7
	s_mov_b32 s95, s91
	v_lshl_add_u64 v[36:37], v[82:83], 0, s[94:95]
	v_mov_b32_e32 v99, v3
	v_lshl_add_u64 v[44:45], v[36:37], 0, v[2:3]
	v_lshl_add_u64 v[40:41], v[36:37], 0, v[98:99]
	global_load_dwordx4 v[36:39], v[40:41], off offset:2240
	s_nop 0
	global_load_dwordx4 v[40:43], v[40:41], off offset:2176
	s_nop 0
	global_load_dwordx4 v[44:47], v[44:45], off offset:2176
	s_branch .LBB0_189
